# static GEMM priority variant: s_setprio 1 for waves 0-3 (instead of 4-7) for the whole GEMM phase, per-cluster flips removed
# baseline (speedup 1.0000x reference)
; #define PG8_STAGE(bufoff, gbase, voff) do { _Pragma("unroll") for (int _i = 0; _i < 2; ++_i) \
;         __builtin_amdgcn_global_load_lds((const unsigned*)((const char*)(gbase) + (voff)[_i]), (PG8_LAS unsigned*)(lds + (bufoff) + ldsw + _i * 8192), 16, 0, 0); } while (0)
; #define PG8_WAIT_V(n) asm volatile("s_waitcnt vmcnt(" #n ")" ::: "memory")
; #define PG8_BAR __builtin_amdgcn_s_barrier()
; template <class Epi, class Sched, bool STAMP = false>
; __device__ __forceinline__ void gemm_phase(PG8_LAS unsigned char* lds, const Gemm g, const Sched& S, const Epi& E, unsigned long long* stamps) {
;     ...
;     for (int i = 0; i < 2; ++i) { int R, C; stage_rc(tid * 16 + i * 8192, R, C); const int Rb = Epi::PERM ? ((R & ~31) + perm32(R & 31)) : R;
;         voffA[i] = (unsigned)(R * K + C) * 2u; voffB[i] = (unsigned)(Rb * K + C) * 2u; }
;     const size_t kstep = (size_t)(BK * 2);
;     const size_t hstep = (size_t)HALF * K * 2;
;     const size_t tstep = 2 * hstep;
;     const unsigned ldsw = (unsigned)wid * 1024u;
;     const int aoff = lds_byte(wr * 64 + fr, fq * 8), boff = lds_byte(wc * 32 + fr, fq * 8);
;     ...
;     Unit cur, nxt; int ui = 0;
;     if (!S.next(0, cur)) return;
;     f32x4 acc[2][2][4][2];
; #pragma unroll
;     for (int a = 0; a < 2; ++a)
; #pragma unroll
;         for (int b = 0; b < 2; ++b)
; #pragma unroll
;             for (int m = 0; m < 4; ++m)
; #pragma unroll
;                 for (int n = 0; n < 2; ++n) acc[a][b][m][n] = (f32x4){0.f, 0.f, 0.f, 0.f};
;     bf16x8 At[4][2], B0[2][2], B1[2][2];
;     const char* cA = (const char*)g.A + (size_t)cur.pm * tstep; const char* cB = (const char*)g.Bt + (size_t)cur.pn * tstep;
;     S.a_ready(cur);
;     PG8_STAGE(PG8_SB(0, 0), cB, voffB); PG8_STAGE(PG8_SA(0, 0), cA, voffA); PG8_STAGE(PG8_SB(0, 1), cB + hstep, voffB); PG8_STAGE(PG8_SA(0, 1), cA + hstep, voffA);
;     if (wr == 1) PG8_BAR;
;     PG8_WAIT_V(4); PG8_BAR;
;     PG8_STAGE(PG8_SB(1, 0), cB + kstep, voffB); PG8_STAGE(PG8_SA(1, 0), cA + kstep, voffA); PG8_STAGE(PG8_SB(1, 1), cB + hstep + kstep, voffB);
;     PG8_WAIT_V(6); PG8_BAR;
.LBB0_736:
	v_mov_b32_e32 v165, v0
	v_lshrrev_b32_e32 v22, 1, v9
	v_lshl_add_u64 v[10:11], s[88:89], 0, v[164:165]
	v_mov_b32_e32 v171, v0
	v_and_b32_e32 v216, 24, v22
	v_lshl_add_u64 v[12:13], s[88:89], 0, v[170:171]
	v_mov_b32_e32 v163, v0
	v_and_b32_e32 v1, 15, v9
	v_lshlrev_b32_e32 v22, 1, v216
	v_lshlrev_b32_e32 v9, 2, v9
	s_add_i32 m0, s80, 0x18000
	v_lshl_add_u64 v[10:11], v[10:11], 0, s[10:11]
	v_lshl_add_u64 v[14:15], s[22:23], 0, v[162:163]
	v_mov_b32_e32 v167, v0
	v_lshl_add_u64 v[18:19], s[0:1], 0, v[164:165]
	v_lshl_add_u64 v[20:21], s[0:1], 0, v[170:171]
	v_lshl_or_b32 v22, v1, 6, v22
	s_lshl_b32 s0, s30, 13
	v_and_b32_e32 v9, 32, v9
	s_waitcnt vmcnt(4)
	s_barrier
	global_load_lds_dwordx4 v[10:11], off
	v_lshl_add_u64 v[10:11], v[12:13], 0, s[10:11]
	s_add_i32 m0, s80, 0x1a000
	s_add_i32 s33, s80, 0x8000
	v_lshl_add_u64 v[16:17], s[22:23], 0, v[166:167]
	v_bitop3_b32 v23, v22, s0, v9 bitop3:0xde
	s_lshl_b32 s0, s28, 5
	global_load_lds_dwordx4 v[10:11], off
	v_lshl_add_u64 v[10:11], v[14:15], 0, s[10:11]
	s_mov_b32 m0, s33
	s_add_i32 s28, s80, 0xa000
	global_load_lds_dwordx4 v[10:11], off
	v_lshl_add_u64 v[10:11], v[16:17], 0, s[10:11]
	s_mov_b32 m0, s28
	v_rcp_iflag_f32_e32 v2, v2
	global_load_lds_dwordx4 v[10:11], off
	s_add_i32 m0, s80, 0x1c000
	v_lshl_add_u64 v[10:11], v[18:19], 0, s[10:11]
	global_load_lds_dwordx4 v[10:11], off
	v_lshl_add_u64 v[10:11], v[20:21], 0, s[10:11]
	s_add_i32 m0, s80, 0x1e000
	v_mul_f32_e32 v2, 0x4f7ffffe, v2
	global_load_lds_dwordx4 v[10:11], off
	v_cvt_u32_f32_e32 v2, v2
	s_and_b32 s72, s0, 0x60
	s_lshl_b32 s0, s72, 7
	v_bitop3_b32 v217, v22, s0, v9 bitop3:0xde
	v_readfirstlane_b32 s1, v2
	v_add_u32_e32 v2, v5, v3
	s_sub_i32 s0, 0, s73
	v_add_lshl_u32 v2, v2, v4, 1
	v_mov_b32_e32 v3, v0
	s_waitcnt vmcnt(6)
	s_mul_i32 s0, s0, s1
	v_lshl_add_u64 v[172:173], s[94:95], 0, v[2:3]
	v_add_u32_e32 v2, v8, v6
	s_lshr_b32 s26, s4, 6
	s_mul_hi_u32 s0, s1, s0
	v_add_lshl_u32 v2, v2, v7, 1
	s_lshl_b32 s5, s30, 6
	s_add_i32 s4, s26, -2
	s_mov_b32 s69, s95
	s_lshr_b32 s34, s68, 3
	s_mov_b32 s70, 0
	s_add_i32 s71, s1, s0
	v_lshl_add_u64 v[174:175], s[94:95], 0, v[2:3]
	v_add_u32_e32 v218, 0, v23
	v_readfirstlane_b32 s98, v169
	s_cmpk_lt_u32 s98, 0x100
	s_cbranch_scc0 .Lg_prio_skip
	s_setprio 1
